# barrier after phase 0 uses the XCD-hierarchical barrier like all other phases instead of the cooperative-groups grid.sync path
# baseline (speedup 1.0000x reference)
; DI unsigned xb_add(unsigned* p, unsigned v) { return __hip_atomic_fetch_add(p, v, __ATOMIC_RELAXED, __HIP_MEMORY_SCOPE_AGENT); }
; DI void xcd_barrier(const XcdBarrier& b, const int tid) {
;     asm volatile("s_waitcnt vmcnt(0)" ::: "memory");
;     __syncthreads();
;     if (tid == 0) {
;         unsigned* bar = b.bar;
;         __builtin_amdgcn_s_waitcnt(0);
;         unsigned nloc = b.st[0], nx = b.st[1];
;         if (nloc == 0u) { xcd_barrier_complete(bar, b.x, nloc, nx); b.st[0] = nloc; b.st[1] = nx; }
;         const unsigned old = xb_add(&bar[XB_XSUB(b.x)], 1u);
;         const unsigned gen = old / nloc;
;         if (old + 1u == (gen + 1u) * nloc) {
; __global__ void __launch_bounds__(512, 2) mega_fwd(Args a_) {
;     ...
;         if (phx + 1 < 2 * ph_hi) { if (ph == 0) grid.sync(); else xcd_barrier(xbar, tid); }
.LBB0_716:
	v_readlane_b32 s4, v255, 20
	v_readlane_b32 s5, v255, 21
	s_mov_b64 s[0:1], -1
	s_and_b64 vcc, exec, s[4:5]
	s_nop 0
	s_waitcnt vmcnt(0)
	v_cmp_eq_u32_e32 vcc, 0, v210
	s_waitcnt vmcnt(0) lgkmcnt(0)
	s_barrier
	s_and_saveexec_b64 s[0:1], vcc
	s_cbranch_execz .LBB0_769
	s_add_i32 s2, 0, 0x20000
	v_mov_b32_e32 v0, s2
	s_waitcnt vmcnt(0) expcnt(0) lgkmcnt(0)
	ds_read_b32 v3, v0
	v_readlane_b32 s4, v254, 36
	s_waitcnt lgkmcnt(0)
	v_cmp_ne_u32_e32 vcc, 0, v3
	v_mov_b32_e32 v0, s4
	ds_read_b32 v2, v0
	s_cbranch_vccnz .LBB0_733
	s_mov_b32 s22, 1
	s_branch .LBB0_721
